# diff loop: LDS fragment reads hoisted up to 28 instructions earlier where the destination buffer is dead (deeper prefetch), waits recomputed
# speedup vs baseline: 1.0079x; 1.0002x over previous
.LBB0_547:
	s_and_b32 s2, s9, 3
	s_mulk_i32 s2, 0x5000
	v_add_u32_e32 v75, s2, v74
	ds_read_b128 v[6:9], v75 offset:8704
	ds_read_b128 v[2:5], v75 offset:8192
	ds_read_b128 v[26:29], v75 offset:4096
	ds_read_b128 v[10:13], v75 offset:10240
	v_exp_f32_e32 v92, v92
	ds_read_b128 v[14:17], v75 offset:10752
	v_exp_f32_e32 v93, v93
	v_exp_f32_e32 v94, v94
	v_exp_f32_e32 v95, v95
	v_exp_f32_e32 v96, v96
	v_exp_f32_e32 v97, v97
	v_exp_f32_e32 v98, v98
	v_exp_f32_e32 v99, v99
	v_cvt_pk_bf16_f32 v70, v92, v93
	v_cvt_pk_bf16_f32 v71, v94, v95
	v_cvt_pk_bf16_f32 v72, v96, v97
	v_cvt_pk_bf16_f32 v73, v98, v99
	ds_read_b128 v[22:25], v75 offset:4608
	s_waitcnt lgkmcnt(4)
	s_nop 0
	v_mfma_f32_32x32x16_bf16 v[156:171], v[2:5], v[70:73], v[156:171]
	s_mov_b32 s10, s8
	s_mov_b32 s11, s8
	s_mov_b32 s9, s8
	v_exp_f32_e32 v100, v100
	v_exp_f32_e32 v101, v101
	v_exp_f32_e32 v102, v102
	ds_read_b128 v[224:227], v75 offset:12288
	v_mfma_f32_32x32x16_bf16 v[140:155], v[6:9], v[70:73], v[140:155]
	v_exp_f32_e32 v103, v103
	v_exp_f32_e32 v104, v104
	v_exp_f32_e32 v105, v105
	ds_read_b128 v[228:231], v75 offset:12800
	v_mfma_f32_16x16x32_bf16 v[214:217], v[58:61], v[70:73], v[214:217]
	v_exp_f32_e32 v106, v106
	v_exp_f32_e32 v107, v107
	v_cvt_pk_bf16_f32 v182, v100, v101
	v_cvt_pk_bf16_f32 v183, v102, v103
	v_cvt_pk_bf16_f32 v184, v104, v105
	v_cvt_pk_bf16_f32 v185, v106, v107
	ds_read_b128 v[100:103], v75 offset:6144
	s_waitcnt lgkmcnt(6)
	v_mfma_f32_32x32x16_bf16 v[34:49], v[26:29], v[178:181], 0
	s_waitcnt lgkmcnt(5)
	v_mfma_f32_32x32x16_bf16 v[156:171], v[10:13], v[182:185], v[156:171]
	v_exp_f32_e32 v76, v76
	v_exp_f32_e32 v77, v77
	v_exp_f32_e32 v78, v78
	ds_read_b128 v[232:235], v75 offset:14336
	s_waitcnt lgkmcnt(5)
	v_mfma_f32_32x32x16_bf16 v[140:155], v[14:17], v[182:185], v[140:155]
	v_exp_f32_e32 v79, v79
	v_exp_f32_e32 v80, v80
	v_exp_f32_e32 v81, v81
	ds_read_b128 v[236:239], v75 offset:14848
	v_mfma_f32_16x16x32_bf16 v[214:217], v[58:61], v[182:185], v[214:217]
	v_exp_f32_e32 v82, v82
	v_exp_f32_e32 v83, v83
	v_cvt_pk_bf16_f32 v70, v76, v77
	v_cvt_pk_bf16_f32 v71, v78, v79
	v_cvt_pk_bf16_f32 v72, v80, v81
	v_cvt_pk_bf16_f32 v73, v82, v83
	s_waitcnt lgkmcnt(5)
	v_mfma_f32_32x32x16_bf16 v[18:33], v[22:25], v[178:181], 0
	s_waitcnt lgkmcnt(4)
	v_mfma_f32_32x32x16_bf16 v[156:171], v[224:227], v[70:73], v[156:171]
	v_exp_f32_e32 v84, v84
	v_exp_f32_e32 v85, v85
	v_exp_f32_e32 v86, v86
	s_waitcnt lgkmcnt(3)
	v_mfma_f32_32x32x16_bf16 v[140:155], v[228:231], v[70:73], v[140:155]
	v_exp_f32_e32 v87, v87
	v_exp_f32_e32 v88, v88
	v_exp_f32_e32 v89, v89
	v_mfma_f32_16x16x32_bf16 v[214:217], v[58:61], v[70:73], v[214:217]
	ds_read_b128 v[70:73], v75 offset:6656
	v_exp_f32_e32 v90, v90
	v_exp_f32_e32 v91, v91
	v_cvt_pk_bf16_f32 v182, v84, v85
	v_cvt_pk_bf16_f32 v183, v86, v87
	v_cvt_pk_bf16_f32 v184, v88, v89
	v_cvt_pk_bf16_f32 v185, v90, v91
	s_waitcnt lgkmcnt(3)
	v_mfma_f32_32x32x16_bf16 v[34:49], v[100:103], v[174:177], v[34:49]
	s_waitcnt lgkmcnt(2)
	v_mfma_f32_32x32x16_bf16 v[156:171], v[232:235], v[182:185], v[156:171]
	s_waitcnt lgkmcnt(1)
	v_mfma_f32_32x32x16_bf16 v[140:155], v[236:239], v[182:185], v[140:155]
	v_mfma_f32_16x16x32_bf16 v[214:217], v[58:61], v[182:185], v[214:217]
	s_waitcnt lgkmcnt(0)
	v_mfma_f32_32x32x16_bf16 v[18:33], v[70:73], v[174:177], v[18:33]
	s_and_b32 s2, s43, 3
	s_mulk_i32 s2, 0x5000
	v_add_u32_e32 v172, s2, v74
	ds_read_b128 v[84:87], v172
	v_exp_f32_e32 v34, v34
	v_exp_f32_e32 v35, v35
	v_exp_f32_e32 v36, v36
	v_exp_f32_e32 v37, v37
	v_exp_f32_e32 v38, v38
	v_exp_f32_e32 v39, v39
	v_exp_f32_e32 v40, v40
	v_exp_f32_e32 v41, v41
	v_cvt_pk_bf16_f32 v70, v34, v35
	v_cvt_pk_bf16_f32 v71, v36, v37
	v_cvt_pk_bf16_f32 v72, v38, v39
	v_cvt_pk_bf16_f32 v73, v40, v41
	ds_read_b128 v[88:91], v172 offset:512
	s_nop 0
	s_nop 0
	v_mfma_f32_32x32x16_bf16 v[124:139], v[2:5], v[70:73], v[124:139]
	v_exp_f32_e32 v42, v42
	v_exp_f32_e32 v43, v43
	v_exp_f32_e32 v44, v44
	s_nop 0
	v_mfma_f32_32x32x16_bf16 v[108:123], v[6:9], v[70:73], v[108:123]
	v_exp_f32_e32 v45, v45
	v_exp_f32_e32 v46, v46
	v_exp_f32_e32 v47, v47
	v_mfma_f32_16x16x32_bf16 v[214:217], v[62:65], v[70:73], v[214:217]
	v_exp_f32_e32 v48, v48
	v_exp_f32_e32 v49, v49
	v_cvt_pk_bf16_f32 v66, v42, v43
	s_waitcnt lgkmcnt(1)
	v_mfma_f32_32x32x16_bf16 v[92:107], v[84:87], v[50:53], 0
	v_cvt_pk_bf16_f32 v67, v44, v45
	v_cvt_pk_bf16_f32 v68, v46, v47
	v_cvt_pk_bf16_f32 v69, v48, v49
	ds_read_b128 v[42:45], v172 offset:2048
	s_nop 0
	s_nop 0
	v_mfma_f32_32x32x16_bf16 v[124:139], v[10:13], v[66:69], v[124:139]
	v_exp_f32_e32 v18, v18
	v_exp_f32_e32 v19, v19
	v_exp_f32_e32 v20, v20
	s_nop 0
	v_mfma_f32_32x32x16_bf16 v[108:123], v[14:17], v[66:69], v[108:123]
	v_exp_f32_e32 v21, v21
	v_exp_f32_e32 v22, v22
	v_exp_f32_e32 v23, v23
	v_mfma_f32_16x16x32_bf16 v[214:217], v[62:65], v[66:69], v[214:217]
	v_exp_f32_e32 v24, v24
	v_exp_f32_e32 v25, v25
	v_cvt_pk_bf16_f32 v70, v18, v19
	s_waitcnt lgkmcnt(1)
	v_mfma_f32_32x32x16_bf16 v[76:91], v[88:91], v[50:53], 0
	v_cvt_pk_bf16_f32 v71, v20, v21
	v_cvt_pk_bf16_f32 v72, v22, v23
	v_cvt_pk_bf16_f32 v73, v24, v25
	s_nop 0
	s_nop 0
	v_mfma_f32_32x32x16_bf16 v[124:139], v[224:227], v[70:73], v[124:139]
	v_exp_f32_e32 v26, v26
	v_exp_f32_e32 v27, v27
	v_exp_f32_e32 v28, v28
	s_nop 0
	v_mfma_f32_32x32x16_bf16 v[108:123], v[228:231], v[70:73], v[108:123]
	v_exp_f32_e32 v29, v29
	v_exp_f32_e32 v30, v30
	v_exp_f32_e32 v31, v31
	v_mfma_f32_16x16x32_bf16 v[214:217], v[62:65], v[70:73], v[214:217]
	v_exp_f32_e32 v32, v32
	v_exp_f32_e32 v33, v33
	v_cvt_pk_bf16_f32 v66, v26, v27
	s_waitcnt lgkmcnt(0)
	v_mfma_f32_32x32x16_bf16 v[92:107], v[42:45], v[54:57], v[92:107]
	ds_read_b128 v[42:45], v172 offset:2560
	v_cvt_pk_bf16_f32 v67, v28, v29
	v_cvt_pk_bf16_f32 v68, v30, v31
	v_cvt_pk_bf16_f32 v69, v32, v33
	s_nop 0
	s_nop 0
	v_mfma_f32_32x32x16_bf16 v[124:139], v[232:235], v[66:69], v[124:139]
	s_nop 0
	v_mfma_f32_32x32x16_bf16 v[108:123], v[236:239], v[66:69], v[108:123]
	v_mfma_f32_16x16x32_bf16 v[214:217], v[62:65], v[66:69], v[214:217]
	s_waitcnt lgkmcnt(0)
	v_mfma_f32_32x32x16_bf16 v[76:91], v[42:45], v[54:57], v[76:91]
	s_add_i32 s2, s43, 1
	s_add_u32 s44, s44, 0x1000
	s_addc_u32 s45, s45, 0
	s_add_u32 s46, s46, 0x2000
	s_addc_u32 s47, s47, 0
	s_cmp_lg_u32 s43, s26
	s_cbranch_scc0 .LBB0_552
	s_mov_b32 s43, s2
	s_add_i32 s9, s43, -1
	s_cmp_ge_u32 s9, s28
	s_mov_b64 s[2:3], -1
	s_cbranch_scc1 .LBB0_539
	s_branch .LBB0_540
